# kendT tile on wave 3, all 8 fragment reads up front with a single LDS wait
# baseline (speedup 1.0000x reference)
.LBB0_598:
	s_or_b64 exec, exec, s[2:3]
	v_and_b32_e32 v66, 31, v166
	v_ashrrev_i32_e32 v152, 2, v166
	v_mad_u32_u24 v67, v66, s69, 16
	v_lshl_add_u32 v60, v66, 2, s70
	v_and_b32_e32 v153, -8, v152
	s_waitcnt lgkmcnt(0)
	s_barrier
	s_nop 0
	v_readfirstlane_b32 s2, v166
	s_cmp_lt_u32 s2, 0xc0
	s_cbranch_scc1 .Lkt_done
	v_and_b32_e32 v62, 31, v166
	v_bfe_u32 v63, v166, 5, 1
	v_lshl_add_u32 v64, v62, 2, s70
	ds_read2_b32 v[64:65], v64 offset0:128 offset1:160
	v_mul_u32_u24_e32 v60, 0x110, v62
	v_lshl_add_u32 v60, v63, 4, v60
	v_add_u32_e32 v60, 0x2210, v60
	ds_read_b128 v[220:223], v60 offset:0
	ds_read_b128 v[224:227], v60 offset:32
	ds_read_b128 v[228:231], v60 offset:64
	ds_read_b128 v[232:235], v60 offset:96
	ds_read_b128 v[236:239], v60 offset:128
	ds_read_b128 v[240:243], v60 offset:160
	ds_read_b128 v[244:247], v60 offset:192
	ds_read_b128 v[248:251], v60 offset:224
	v_mul_u32_u24_e32 v61, 0x280, v63
	v_lshl_add_u32 v61, v62, 1, v61
	v_add_u32_e32 v61, 0x8810, v61
	s_waitcnt lgkmcnt(0)
	v_mul_f32_e32 v64, v64, v65
	v_lshlrev_b32_e32 v62, 16, v220
	v_and_b32_e32 v63, 0xffff0000, v220
	v_mul_f32_e32 v62, v64, v62
	v_mul_f32_e32 v63, v64, v63
	v_cvt_pk_bf16_f32 v62, v62, v62
	v_cvt_pk_bf16_f32 v63, v63, v63
	ds_write_b16 v61, v62 offset:0
	ds_write_b16 v61, v63 offset:80
	v_lshlrev_b32_e32 v66, 16, v221
	v_and_b32_e32 v67, 0xffff0000, v221
	v_mul_f32_e32 v66, v64, v66
	v_mul_f32_e32 v67, v64, v67
	v_cvt_pk_bf16_f32 v66, v66, v66
	v_cvt_pk_bf16_f32 v67, v67, v67
	ds_write_b16 v61, v66 offset:160
	ds_write_b16 v61, v67 offset:240
	v_lshlrev_b32_e32 v152, 16, v222
	v_and_b32_e32 v153, 0xffff0000, v222
	v_mul_f32_e32 v152, v64, v152
	v_mul_f32_e32 v153, v64, v153
	v_cvt_pk_bf16_f32 v152, v152, v152
	v_cvt_pk_bf16_f32 v153, v153, v153
	ds_write_b16 v61, v152 offset:320
	ds_write_b16 v61, v153 offset:400
	v_lshlrev_b32_e32 v154, 16, v223
	v_and_b32_e32 v155, 0xffff0000, v223
	v_mul_f32_e32 v154, v64, v154
	v_mul_f32_e32 v155, v64, v155
	v_cvt_pk_bf16_f32 v154, v154, v154
	v_cvt_pk_bf16_f32 v155, v155, v155
	ds_write_b16 v61, v154 offset:480
	ds_write_b16 v61, v155 offset:560
	v_lshlrev_b32_e32 v62, 16, v224
	v_and_b32_e32 v63, 0xffff0000, v224
	v_mul_f32_e32 v62, v64, v62
	v_mul_f32_e32 v63, v64, v63
	v_cvt_pk_bf16_f32 v62, v62, v62
	v_cvt_pk_bf16_f32 v63, v63, v63
	ds_write_b16 v61, v62 offset:1280
	ds_write_b16 v61, v63 offset:1360
	v_lshlrev_b32_e32 v66, 16, v225
	v_and_b32_e32 v67, 0xffff0000, v225
	v_mul_f32_e32 v66, v64, v66
	v_mul_f32_e32 v67, v64, v67
	v_cvt_pk_bf16_f32 v66, v66, v66
	v_cvt_pk_bf16_f32 v67, v67, v67
	ds_write_b16 v61, v66 offset:1440
	ds_write_b16 v61, v67 offset:1520
	v_lshlrev_b32_e32 v152, 16, v226
	v_and_b32_e32 v153, 0xffff0000, v226
	v_mul_f32_e32 v152, v64, v152
	v_mul_f32_e32 v153, v64, v153
	v_cvt_pk_bf16_f32 v152, v152, v152
	v_cvt_pk_bf16_f32 v153, v153, v153
	ds_write_b16 v61, v152 offset:1600
	ds_write_b16 v61, v153 offset:1680
	v_lshlrev_b32_e32 v154, 16, v227
	v_and_b32_e32 v155, 0xffff0000, v227
	v_mul_f32_e32 v154, v64, v154
	v_mul_f32_e32 v155, v64, v155
	v_cvt_pk_bf16_f32 v154, v154, v154
	v_cvt_pk_bf16_f32 v155, v155, v155
	ds_write_b16 v61, v154 offset:1760
	ds_write_b16 v61, v155 offset:1840
	v_lshlrev_b32_e32 v62, 16, v228
	v_and_b32_e32 v63, 0xffff0000, v228
	v_mul_f32_e32 v62, v64, v62
	v_mul_f32_e32 v63, v64, v63
	v_cvt_pk_bf16_f32 v62, v62, v62
	v_cvt_pk_bf16_f32 v63, v63, v63
	ds_write_b16 v61, v62 offset:2560
	ds_write_b16 v61, v63 offset:2640
	v_lshlrev_b32_e32 v66, 16, v229
	v_and_b32_e32 v67, 0xffff0000, v229
	v_mul_f32_e32 v66, v64, v66
	v_mul_f32_e32 v67, v64, v67
	v_cvt_pk_bf16_f32 v66, v66, v66
	v_cvt_pk_bf16_f32 v67, v67, v67
	ds_write_b16 v61, v66 offset:2720
	ds_write_b16 v61, v67 offset:2800
	v_lshlrev_b32_e32 v152, 16, v230
	v_and_b32_e32 v153, 0xffff0000, v230
	v_mul_f32_e32 v152, v64, v152
	v_mul_f32_e32 v153, v64, v153
	v_cvt_pk_bf16_f32 v152, v152, v152
	v_cvt_pk_bf16_f32 v153, v153, v153
	ds_write_b16 v61, v152 offset:2880
	ds_write_b16 v61, v153 offset:2960
	v_lshlrev_b32_e32 v154, 16, v231
	v_and_b32_e32 v155, 0xffff0000, v231
	v_mul_f32_e32 v154, v64, v154
	v_mul_f32_e32 v155, v64, v155
	v_cvt_pk_bf16_f32 v154, v154, v154
	v_cvt_pk_bf16_f32 v155, v155, v155
	ds_write_b16 v61, v154 offset:3040
	ds_write_b16 v61, v155 offset:3120
	v_lshlrev_b32_e32 v62, 16, v232
	v_and_b32_e32 v63, 0xffff0000, v232
	v_mul_f32_e32 v62, v64, v62
	v_mul_f32_e32 v63, v64, v63
	v_cvt_pk_bf16_f32 v62, v62, v62
	v_cvt_pk_bf16_f32 v63, v63, v63
	ds_write_b16 v61, v62 offset:3840
	ds_write_b16 v61, v63 offset:3920
	v_lshlrev_b32_e32 v66, 16, v233
	v_and_b32_e32 v67, 0xffff0000, v233
	v_mul_f32_e32 v66, v64, v66
	v_mul_f32_e32 v67, v64, v67
	v_cvt_pk_bf16_f32 v66, v66, v66
	v_cvt_pk_bf16_f32 v67, v67, v67
	ds_write_b16 v61, v66 offset:4000
	ds_write_b16 v61, v67 offset:4080
	v_lshlrev_b32_e32 v152, 16, v234
	v_and_b32_e32 v153, 0xffff0000, v234
	v_mul_f32_e32 v152, v64, v152
	v_mul_f32_e32 v153, v64, v153
	v_cvt_pk_bf16_f32 v152, v152, v152
	v_cvt_pk_bf16_f32 v153, v153, v153
	ds_write_b16 v61, v152 offset:4160
	ds_write_b16 v61, v153 offset:4240
	v_lshlrev_b32_e32 v154, 16, v235
	v_and_b32_e32 v155, 0xffff0000, v235
	v_mul_f32_e32 v154, v64, v154
	v_mul_f32_e32 v155, v64, v155
	v_cvt_pk_bf16_f32 v154, v154, v154
	v_cvt_pk_bf16_f32 v155, v155, v155
	ds_write_b16 v61, v154 offset:4320
	ds_write_b16 v61, v155 offset:4400
	v_lshlrev_b32_e32 v62, 16, v236
	v_and_b32_e32 v63, 0xffff0000, v236
	v_mul_f32_e32 v62, v64, v62
	v_mul_f32_e32 v63, v64, v63
	v_cvt_pk_bf16_f32 v62, v62, v62
	v_cvt_pk_bf16_f32 v63, v63, v63
	ds_write_b16 v61, v62 offset:5120
	ds_write_b16 v61, v63 offset:5200
	v_lshlrev_b32_e32 v66, 16, v237
	v_and_b32_e32 v67, 0xffff0000, v237
	v_mul_f32_e32 v66, v64, v66
	v_mul_f32_e32 v67, v64, v67
	v_cvt_pk_bf16_f32 v66, v66, v66
	v_cvt_pk_bf16_f32 v67, v67, v67
	ds_write_b16 v61, v66 offset:5280
	ds_write_b16 v61, v67 offset:5360
	v_lshlrev_b32_e32 v152, 16, v238
	v_and_b32_e32 v153, 0xffff0000, v238
	v_mul_f32_e32 v152, v64, v152
	v_mul_f32_e32 v153, v64, v153
	v_cvt_pk_bf16_f32 v152, v152, v152
	v_cvt_pk_bf16_f32 v153, v153, v153
	ds_write_b16 v61, v152 offset:5440
	ds_write_b16 v61, v153 offset:5520
	v_lshlrev_b32_e32 v154, 16, v239
	v_and_b32_e32 v155, 0xffff0000, v239
	v_mul_f32_e32 v154, v64, v154
	v_mul_f32_e32 v155, v64, v155
	v_cvt_pk_bf16_f32 v154, v154, v154
	v_cvt_pk_bf16_f32 v155, v155, v155
	ds_write_b16 v61, v154 offset:5600
	ds_write_b16 v61, v155 offset:5680
	v_lshlrev_b32_e32 v62, 16, v240
	v_and_b32_e32 v63, 0xffff0000, v240
	v_mul_f32_e32 v62, v64, v62
	v_mul_f32_e32 v63, v64, v63
	v_cvt_pk_bf16_f32 v62, v62, v62
	v_cvt_pk_bf16_f32 v63, v63, v63
	ds_write_b16 v61, v62 offset:6400
	ds_write_b16 v61, v63 offset:6480
	v_lshlrev_b32_e32 v66, 16, v241
	v_and_b32_e32 v67, 0xffff0000, v241
	v_mul_f32_e32 v66, v64, v66
	v_mul_f32_e32 v67, v64, v67
	v_cvt_pk_bf16_f32 v66, v66, v66
	v_cvt_pk_bf16_f32 v67, v67, v67
	ds_write_b16 v61, v66 offset:6560
	ds_write_b16 v61, v67 offset:6640
	v_lshlrev_b32_e32 v152, 16, v242
	v_and_b32_e32 v153, 0xffff0000, v242
	v_mul_f32_e32 v152, v64, v152
	v_mul_f32_e32 v153, v64, v153
	v_cvt_pk_bf16_f32 v152, v152, v152
	v_cvt_pk_bf16_f32 v153, v153, v153
	ds_write_b16 v61, v152 offset:6720
	ds_write_b16 v61, v153 offset:6800
	v_lshlrev_b32_e32 v154, 16, v243
	v_and_b32_e32 v155, 0xffff0000, v243
	v_mul_f32_e32 v154, v64, v154
	v_mul_f32_e32 v155, v64, v155
	v_cvt_pk_bf16_f32 v154, v154, v154
	v_cvt_pk_bf16_f32 v155, v155, v155
	ds_write_b16 v61, v154 offset:6880
	ds_write_b16 v61, v155 offset:6960
	v_lshlrev_b32_e32 v62, 16, v244
	v_and_b32_e32 v63, 0xffff0000, v244
	v_mul_f32_e32 v62, v64, v62
	v_mul_f32_e32 v63, v64, v63
	v_cvt_pk_bf16_f32 v62, v62, v62
	v_cvt_pk_bf16_f32 v63, v63, v63
	ds_write_b16 v61, v62 offset:7680
	ds_write_b16 v61, v63 offset:7760
	v_lshlrev_b32_e32 v66, 16, v245
	v_and_b32_e32 v67, 0xffff0000, v245
	v_mul_f32_e32 v66, v64, v66
	v_mul_f32_e32 v67, v64, v67
	v_cvt_pk_bf16_f32 v66, v66, v66
	v_cvt_pk_bf16_f32 v67, v67, v67
	ds_write_b16 v61, v66 offset:7840
	ds_write_b16 v61, v67 offset:7920
	v_lshlrev_b32_e32 v152, 16, v246
	v_and_b32_e32 v153, 0xffff0000, v246
	v_mul_f32_e32 v152, v64, v152
	v_mul_f32_e32 v153, v64, v153
	v_cvt_pk_bf16_f32 v152, v152, v152
	v_cvt_pk_bf16_f32 v153, v153, v153
	ds_write_b16 v61, v152 offset:8000
	ds_write_b16 v61, v153 offset:8080
	v_lshlrev_b32_e32 v154, 16, v247
	v_and_b32_e32 v155, 0xffff0000, v247
	v_mul_f32_e32 v154, v64, v154
	v_mul_f32_e32 v155, v64, v155
	v_cvt_pk_bf16_f32 v154, v154, v154
	v_cvt_pk_bf16_f32 v155, v155, v155
	ds_write_b16 v61, v154 offset:8160
	ds_write_b16 v61, v155 offset:8240
	v_lshlrev_b32_e32 v62, 16, v248
	v_and_b32_e32 v63, 0xffff0000, v248
	v_mul_f32_e32 v62, v64, v62
	v_mul_f32_e32 v63, v64, v63
	v_cvt_pk_bf16_f32 v62, v62, v62
	v_cvt_pk_bf16_f32 v63, v63, v63
	ds_write_b16 v61, v62 offset:8960
	ds_write_b16 v61, v63 offset:9040
	v_lshlrev_b32_e32 v66, 16, v249
	v_and_b32_e32 v67, 0xffff0000, v249
	v_mul_f32_e32 v66, v64, v66
	v_mul_f32_e32 v67, v64, v67
	v_cvt_pk_bf16_f32 v66, v66, v66
	v_cvt_pk_bf16_f32 v67, v67, v67
	ds_write_b16 v61, v66 offset:9120
	ds_write_b16 v61, v67 offset:9200
	v_lshlrev_b32_e32 v152, 16, v250
	v_and_b32_e32 v153, 0xffff0000, v250
	v_mul_f32_e32 v152, v64, v152
	v_mul_f32_e32 v153, v64, v153
	v_cvt_pk_bf16_f32 v152, v152, v152
	v_cvt_pk_bf16_f32 v153, v153, v153
	ds_write_b16 v61, v152 offset:9280
	ds_write_b16 v61, v153 offset:9360
	v_lshlrev_b32_e32 v154, 16, v251
	v_and_b32_e32 v155, 0xffff0000, v251
	v_mul_f32_e32 v154, v64, v154
	v_mul_f32_e32 v155, v64, v155
	v_cvt_pk_bf16_f32 v154, v154, v154
	v_cvt_pk_bf16_f32 v155, v155, v155
	ds_write_b16 v61, v154 offset:9440
	ds_write_b16 v61, v155 offset:9520
